# G2 phase: RG-LRU inter-chunk scan (8 workgroups, latency bound) runs before the GLA state scan instead of after it, so it overlaps the other workgroups' streaming; on top of v76
# speedup vs baseline: 1.0032x; 1.0028x over previous
_Z14fwd_megakernel6Paramsiii:
	s_mov_b32 s100, 0
	s_load_dwordx2 s[4:5], s[0:1], 0xf0
	s_add_u32 s6, s0, 0xf0
	s_addc_u32 s7, s1, 0
	v_mov_b32_e32 v1, 0
	v_and_b32_e32 v180, 0x3ff, v0
	s_waitcnt lgkmcnt(0)
	v_writelane_b32 v249, s4, 0
	s_cmp_lt_u32 s2, s4
	s_nop 0
	v_writelane_b32 v249, s5, 1
	v_writelane_b32 v249, s2, 2
	s_cselect_b32 s2, 12, 18
	s_add_u32 s2, s6, s2
	v_writelane_b32 v249, s6, 3
	s_addc_u32 s3, s7, 0
	global_load_ushort v2, v1, s[2:3]
	s_load_dword s31, s[0:1], 0xf8
	s_load_dwordx8 s[20:27], s[0:1], 0xc0
	v_writelane_b32 v249, s7, 4
	v_cmp_eq_u32_e64 s[4:5], 0, v180
	s_waitcnt vmcnt(0)
	v_readfirstlane_b32 s78, v2
	s_mov_b64 s[2:3], exec
	v_writelane_b32 v249, s4, 5
	s_nop 1
	v_writelane_b32 v249, s5, 6
	s_and_b64 s[4:5], s[2:3], s[4:5]
	s_mov_b64 exec, s[4:5]
	s_cbranch_execz .LBB0_2
	v_mov_b32_e32 v2, 0x20800
	ds_write_b32 v2, v1
	v_mov_b32_e32 v2, 0x20804
	ds_write_b32 v2, v1

.Lg2_top:
	v_mov_b32_e32 v4, v180
	v_readlane_b32 s0, v254, 14
	v_readlane_b32 s1, v254, 15
	v_ashrrev_i32_e32 v5, 31, v4
	s_nop 0
	v_lshl_add_u64 v[2:3], s[0:1], 0, v[4:5]
	s_cmp_eq_u32 s100, 0
	s_cbranch_scc0 .Lg2_scan
	s_mov_b32 s100, 1
	s_branch .Lg2_lru
.Lg2_scan:
	s_mov_b64 s[0:1], 0x40000
	v_cmp_gt_i64_e32 vcc, s[0:1], v[2:3]
	s_and_saveexec_b64 s[0:1], vcc
	s_cbranch_execz .LBB0_123
	s_mov_b64 s[2:3], 0
	v_mov_b64_e32 v[6:7], v[2:3]

.LBB0_123:
	s_or_b64 exec, exec, s[0:1]
	s_mov_b32 s100, 0
	s_branch .LBB0_129
.Lg2_lru:
	s_mov_b64 s[0:1], 0x1000
	v_cmp_gt_i64_e32 vcc, s[0:1], v[2:3]
	s_and_saveexec_b64 s[0:1], vcc
	s_cbranch_execz .LBB0_128
	v_readlane_b32 s2, v254, 18
	s_nop 1
	v_add_u16_e32 v0, s2, v4
	s_mov_b64 s[2:3], 0

.LBB0_128:
	s_or_b64 exec, exec, s[0:1]
	s_branch .Lg2_top
